# branch-GEMM epilogue as one contiguous sequence, each block loads its four operands together
# speedup vs baseline: 1.0080x; 1.0023x over previous
.LBB0_90:
	v_mov_b32_e32 v136, s88
	ds_read_b32 v136, v136
	v_readlane_b32 s2, v254, 44
	v_mov_b32_e32 v151, v153
	s_mov_b64 s[58:59], -1
	s_mov_b64 s[56:57], 0
	s_waitcnt lgkmcnt(0)
	v_readfirstlane_b32 s48, v136
	v_mov_b32_e32 v136, s89
	ds_read_b32 v136, v136
	s_add_u32 s52, s48, 0x2100000
	s_waitcnt lgkmcnt(0)
	v_readfirstlane_b32 s49, v136
	v_mov_b32_e32 v136, s2
	ds_read_b32 v136, v136
	v_readlane_b32 s2, v254, 45
	s_addc_u32 s53, s49, 0
	s_add_u32 s46, s48, 0x158d0000
	s_addc_u32 s47, s49, 0
	s_waitcnt lgkmcnt(0)
	v_readfirstlane_b32 s42, v136
	v_mov_b32_e32 v136, s2
	ds_read_b32 v136, v136
	v_readlane_b32 s2, v254, 31
	s_add_u32 s40, s48, 0xc600000
	s_addc_u32 s41, s49, 0
	s_add_u32 s36, s48, 0xe700000
	s_waitcnt lgkmcnt(0)
	v_readfirstlane_b32 s43, v136
	v_mov_b32_e32 v136, s2
	ds_read_b32 v136, v136
	v_readlane_b32 s2, v254, 46
	s_addc_u32 s37, s49, 0
	s_add_u32 s34, s48, 0x6300000
	s_addc_u32 s35, s49, 0
	s_waitcnt lgkmcnt(0)
	v_readfirstlane_b32 s65, v136
	v_mov_b32_e32 v136, s2
	ds_read_b32 v136, v136
	v_readlane_b32 s2, v254, 39
	s_add_u32 s38, s48, 0x4200000
	s_addc_u32 s39, s49, 0
	s_add_u32 s50, s48, 0x15af4000
	s_waitcnt lgkmcnt(0)
	v_readfirstlane_b32 s66, v136
	v_mov_b32_e32 v136, s2
	ds_read_b32 v136, v136
	v_readlane_b32 s2, v254, 48
	s_addc_u32 s51, s49, 0
	s_lshl_b32 s62, s10, 8
	s_lshl_b32 s27, s67, 8
	s_waitcnt lgkmcnt(0)
	v_readfirstlane_b32 s44, v136
	v_mov_b32_e32 v136, s2
	v_readlane_b32 s2, v254, 40
	s_add_i32 s62, s62, s2
	s_ashr_i32 s2, s62, 13
	ds_read_b32 v136, v136
	s_mul_i32 s54, s2, 0x1800
	v_readlane_b32 s2, v254, 26
	s_ashr_i32 s55, s54, 31
	s_mul_i32 s2, s2, 0x12000
	s_add_u32 s2, s48, s2
	v_or_b32_e32 v138, s62, v157
	s_addc_u32 s3, s49, 0
	v_ashrrev_i32_e32 v139, 31, v138
	s_add_u32 s30, s2, 0x15ad0000
	s_waitcnt lgkmcnt(0)
	v_readfirstlane_b32 s45, v136
	v_lshlrev_b64 v[136:137], 13, v[138:139]
	v_add_u32_e32 v150, 0xffffc000, v138
	s_addc_u32 s31, s3, 0
	v_lshl_add_u64 v[148:149], s[52:53], 0, v[136:137]
	v_cmp_gt_i32_e64 s[10:11], s92, v138
	v_cmp_lt_i32_e64 s[8:9], s80, v138
	v_lshlrev_b64 v[146:147], 10, v[150:151]
	v_lshlrev_b64 v[142:143], 10, v[138:139]
	v_or_b32_e32 v136, s27, v161
	s_cmp_lt_i32 s79, 22
	s_cbranch_scc1 .Lfb_no
	s_cmp_gt_i32 s79, 24
	s_cbranch_scc1 .Lfb_no
	v_ashrrev_i32_e32 v137, 31, v136
	v_lshl_add_u64 v[140:141], v[142:143], 0, v[136:137]
	v_lshlrev_b64 v[140:141], 1, v[140:141]
	s_cmp_eq_u32 s79, 23
	s_cselect_b32 s2, s34, s40
	s_cselect_b32 s3, s35, s41
	s_cmp_eq_u32 s79, 22
	s_cselect_b32 s2, s38, s2
	s_cselect_b32 s3, s39, s3
	v_lshl_add_u64 v[244:245], s[2:3], 0, v[140:141]
	v_lshl_add_u64 v[246:247], s[36:37], 0, v[140:141]
	s_cbranch_scc1 .Lfb_k0
	v_mov_b32_e32 v236, v244
	v_mov_b32_e32 v237, v245
	global_load_dwordx2 v[194:195], v[236:237], off
	global_load_dwordx2 v[196:197], v[236:237], off offset:32
	v_mov_b32_e32 v236, v246
	v_mov_b32_e32 v237, v247
	global_load_dwordx2 v[198:199], v[236:237], off
	global_load_dwordx2 v[200:201], v[236:237], off offset:32
	s_waitcnt vmcnt(0)
	v_lshlrev_b32_e32 v230, 16, v194
	v_and_b32_e32 v231, 0xffff0000, v194
	v_lshlrev_b32_e32 v232, 16, v195
	v_and_b32_e32 v233, 0xffff0000, v195
	v_lshlrev_b32_e32 v234, 16, v198
	v_and_b32_e32 v235, 0xffff0000, v198
	v_lshlrev_b32_e32 v236, 16, v199
	v_and_b32_e32 v237, 0xffff0000, v199
	v_pk_fma_f32 v[230:231], v[124:125], v[230:231], v[234:235]
	v_pk_fma_f32 v[232:233], v[126:127], v[232:233], v[236:237]
	v_cvt_pk_bf16_f32 v230, v230, v231
	v_cvt_pk_bf16_f32 v231, v232, v233
	v_lshlrev_b32_e32 v194, 16, v196
	v_and_b32_e32 v195, 0xffff0000, v196
	v_lshlrev_b32_e32 v198, 16, v197
	v_and_b32_e32 v199, 0xffff0000, v197
	v_lshlrev_b32_e32 v234, 16, v200
	v_and_b32_e32 v235, 0xffff0000, v200
	v_lshlrev_b32_e32 v236, 16, v201
	v_and_b32_e32 v237, 0xffff0000, v201
	v_pk_fma_f32 v[194:195], v[120:121], v[194:195], v[234:235]
	v_pk_fma_f32 v[198:199], v[122:123], v[198:199], v[236:237]
	v_cvt_pk_bf16_f32 v232, v194, v195
	v_cvt_pk_bf16_f32 v233, v198, v199
	v_mov_b32_e32 v236, v246
	v_mov_b32_e32 v237, v247
	global_store_dwordx2 v[236:237], v[230:231], off
	global_store_dwordx2 v[236:237], v[232:233], off offset:32
	v_add_co_u32_e32 v236, vcc, 0x100, v244
	v_addc_co_u32_e32 v237, vcc, 0, v245, vcc
	global_load_dwordx2 v[194:195], v[236:237], off
	global_load_dwordx2 v[196:197], v[236:237], off offset:32
	v_add_co_u32_e32 v236, vcc, 0x100, v246
	v_addc_co_u32_e32 v237, vcc, 0, v247, vcc
	global_load_dwordx2 v[198:199], v[236:237], off
	global_load_dwordx2 v[200:201], v[236:237], off offset:32
	s_waitcnt vmcnt(0)
	v_lshlrev_b32_e32 v230, 16, v194
	v_and_b32_e32 v231, 0xffff0000, v194
	v_lshlrev_b32_e32 v232, 16, v195
	v_and_b32_e32 v233, 0xffff0000, v195
	v_lshlrev_b32_e32 v234, 16, v198
	v_and_b32_e32 v235, 0xffff0000, v198
	v_lshlrev_b32_e32 v236, 16, v199
	v_and_b32_e32 v237, 0xffff0000, v199
	v_pk_fma_f32 v[230:231], v[116:117], v[230:231], v[234:235]
	v_pk_fma_f32 v[232:233], v[118:119], v[232:233], v[236:237]
	v_cvt_pk_bf16_f32 v230, v230, v231
	v_cvt_pk_bf16_f32 v231, v232, v233
	v_lshlrev_b32_e32 v194, 16, v196
	v_and_b32_e32 v195, 0xffff0000, v196
	v_lshlrev_b32_e32 v198, 16, v197
	v_and_b32_e32 v199, 0xffff0000, v197
	v_lshlrev_b32_e32 v234, 16, v200
	v_and_b32_e32 v235, 0xffff0000, v200
	v_lshlrev_b32_e32 v236, 16, v201
	v_and_b32_e32 v237, 0xffff0000, v201
	v_pk_fma_f32 v[194:195], v[112:113], v[194:195], v[234:235]
	v_pk_fma_f32 v[198:199], v[114:115], v[198:199], v[236:237]
	v_cvt_pk_bf16_f32 v232, v194, v195
	v_cvt_pk_bf16_f32 v233, v198, v199
	v_add_co_u32_e32 v236, vcc, 0x100, v246
	v_addc_co_u32_e32 v237, vcc, 0, v247, vcc
	global_store_dwordx2 v[236:237], v[230:231], off
	global_store_dwordx2 v[236:237], v[232:233], off offset:32
	v_add_co_u32_e32 v236, vcc, 0x8000, v244
	v_addc_co_u32_e32 v237, vcc, 0, v245, vcc
	global_load_dwordx2 v[194:195], v[236:237], off
	global_load_dwordx2 v[196:197], v[236:237], off offset:32
	v_add_co_u32_e32 v236, vcc, 0x8000, v246
	v_addc_co_u32_e32 v237, vcc, 0, v247, vcc
	global_load_dwordx2 v[198:199], v[236:237], off
	global_load_dwordx2 v[200:201], v[236:237], off offset:32
	s_waitcnt vmcnt(0)
	v_lshlrev_b32_e32 v230, 16, v194
	v_and_b32_e32 v231, 0xffff0000, v194
	v_lshlrev_b32_e32 v232, 16, v195
	v_and_b32_e32 v233, 0xffff0000, v195
	v_lshlrev_b32_e32 v234, 16, v198
	v_and_b32_e32 v235, 0xffff0000, v198
	v_lshlrev_b32_e32 v236, 16, v199
	v_and_b32_e32 v237, 0xffff0000, v199
	v_pk_fma_f32 v[230:231], v[108:109], v[230:231], v[234:235]
	v_pk_fma_f32 v[232:233], v[110:111], v[232:233], v[236:237]
	v_cvt_pk_bf16_f32 v230, v230, v231
	v_cvt_pk_bf16_f32 v231, v232, v233
	v_lshlrev_b32_e32 v194, 16, v196
	v_and_b32_e32 v195, 0xffff0000, v196
	v_lshlrev_b32_e32 v198, 16, v197
	v_and_b32_e32 v199, 0xffff0000, v197
	v_lshlrev_b32_e32 v234, 16, v200
	v_and_b32_e32 v235, 0xffff0000, v200
	v_lshlrev_b32_e32 v236, 16, v201
	v_and_b32_e32 v237, 0xffff0000, v201
	v_pk_fma_f32 v[194:195], v[104:105], v[194:195], v[234:235]
	v_pk_fma_f32 v[198:199], v[106:107], v[198:199], v[236:237]
	v_cvt_pk_bf16_f32 v232, v194, v195
	v_cvt_pk_bf16_f32 v233, v198, v199
	v_add_co_u32_e32 v236, vcc, 0x8000, v246
	v_addc_co_u32_e32 v237, vcc, 0, v247, vcc
	global_store_dwordx2 v[236:237], v[230:231], off
	global_store_dwordx2 v[236:237], v[232:233], off offset:32
	v_add_co_u32_e32 v236, vcc, 0x8100, v244
	v_addc_co_u32_e32 v237, vcc, 0, v245, vcc
	global_load_dwordx2 v[194:195], v[236:237], off
	global_load_dwordx2 v[196:197], v[236:237], off offset:32
	v_add_co_u32_e32 v236, vcc, 0x8100, v246
	v_addc_co_u32_e32 v237, vcc, 0, v247, vcc
	global_load_dwordx2 v[198:199], v[236:237], off
	global_load_dwordx2 v[200:201], v[236:237], off offset:32
	s_waitcnt vmcnt(0)
	v_lshlrev_b32_e32 v230, 16, v194
	v_and_b32_e32 v231, 0xffff0000, v194
	v_lshlrev_b32_e32 v232, 16, v195
	v_and_b32_e32 v233, 0xffff0000, v195
	v_lshlrev_b32_e32 v234, 16, v198
	v_and_b32_e32 v235, 0xffff0000, v198
	v_lshlrev_b32_e32 v236, 16, v199
	v_and_b32_e32 v237, 0xffff0000, v199
	v_pk_fma_f32 v[230:231], v[100:101], v[230:231], v[234:235]
	v_pk_fma_f32 v[232:233], v[102:103], v[232:233], v[236:237]
	v_cvt_pk_bf16_f32 v230, v230, v231
	v_cvt_pk_bf16_f32 v231, v232, v233
	v_lshlrev_b32_e32 v194, 16, v196
	v_and_b32_e32 v195, 0xffff0000, v196
	v_lshlrev_b32_e32 v198, 16, v197
	v_and_b32_e32 v199, 0xffff0000, v197
	v_lshlrev_b32_e32 v234, 16, v200
	v_and_b32_e32 v235, 0xffff0000, v200
	v_lshlrev_b32_e32 v236, 16, v201
	v_and_b32_e32 v237, 0xffff0000, v201
	v_pk_fma_f32 v[194:195], v[96:97], v[194:195], v[234:235]
	v_pk_fma_f32 v[198:199], v[98:99], v[198:199], v[236:237]
	v_cvt_pk_bf16_f32 v232, v194, v195
	v_cvt_pk_bf16_f32 v233, v198, v199
	v_add_co_u32_e32 v236, vcc, 0x8100, v246
	v_addc_co_u32_e32 v237, vcc, 0, v247, vcc
	global_store_dwordx2 v[236:237], v[230:231], off
	global_store_dwordx2 v[236:237], v[232:233], off offset:32
	v_add_co_u32_e32 v236, vcc, 0x10000, v244
	v_addc_co_u32_e32 v237, vcc, 0, v245, vcc
	global_load_dwordx2 v[194:195], v[236:237], off
	global_load_dwordx2 v[196:197], v[236:237], off offset:32
	v_add_co_u32_e32 v236, vcc, 0x10000, v246
	v_addc_co_u32_e32 v237, vcc, 0, v247, vcc
	global_load_dwordx2 v[198:199], v[236:237], off
	global_load_dwordx2 v[200:201], v[236:237], off offset:32
	s_waitcnt vmcnt(0)
	v_lshlrev_b32_e32 v230, 16, v194
	v_and_b32_e32 v231, 0xffff0000, v194
	v_lshlrev_b32_e32 v232, 16, v195
	v_and_b32_e32 v233, 0xffff0000, v195
	v_lshlrev_b32_e32 v234, 16, v198
	v_and_b32_e32 v235, 0xffff0000, v198
	v_lshlrev_b32_e32 v236, 16, v199
	v_and_b32_e32 v237, 0xffff0000, v199
	v_pk_fma_f32 v[230:231], v[92:93], v[230:231], v[234:235]
	v_pk_fma_f32 v[232:233], v[94:95], v[232:233], v[236:237]
	v_cvt_pk_bf16_f32 v230, v230, v231
	v_cvt_pk_bf16_f32 v231, v232, v233
	v_lshlrev_b32_e32 v194, 16, v196
	v_and_b32_e32 v195, 0xffff0000, v196
	v_lshlrev_b32_e32 v198, 16, v197
	v_and_b32_e32 v199, 0xffff0000, v197
	v_lshlrev_b32_e32 v234, 16, v200
	v_and_b32_e32 v235, 0xffff0000, v200
	v_lshlrev_b32_e32 v236, 16, v201
	v_and_b32_e32 v237, 0xffff0000, v201
	v_pk_fma_f32 v[194:195], v[88:89], v[194:195], v[234:235]
	v_pk_fma_f32 v[198:199], v[90:91], v[198:199], v[236:237]
	v_cvt_pk_bf16_f32 v232, v194, v195
	v_cvt_pk_bf16_f32 v233, v198, v199
	v_add_co_u32_e32 v236, vcc, 0x10000, v246
	v_addc_co_u32_e32 v237, vcc, 0, v247, vcc
	global_store_dwordx2 v[236:237], v[230:231], off
	global_store_dwordx2 v[236:237], v[232:233], off offset:32
	v_add_co_u32_e32 v236, vcc, 0x10100, v244
	v_addc_co_u32_e32 v237, vcc, 0, v245, vcc
	global_load_dwordx2 v[194:195], v[236:237], off
	global_load_dwordx2 v[196:197], v[236:237], off offset:32
	v_add_co_u32_e32 v236, vcc, 0x10100, v246
	v_addc_co_u32_e32 v237, vcc, 0, v247, vcc
	global_load_dwordx2 v[198:199], v[236:237], off
	global_load_dwordx2 v[200:201], v[236:237], off offset:32
	s_waitcnt vmcnt(0)
	v_lshlrev_b32_e32 v230, 16, v194
	v_and_b32_e32 v231, 0xffff0000, v194
	v_lshlrev_b32_e32 v232, 16, v195
	v_and_b32_e32 v233, 0xffff0000, v195
	v_lshlrev_b32_e32 v234, 16, v198
	v_and_b32_e32 v235, 0xffff0000, v198
	v_lshlrev_b32_e32 v236, 16, v199
	v_and_b32_e32 v237, 0xffff0000, v199
	v_pk_fma_f32 v[230:231], v[84:85], v[230:231], v[234:235]
	v_pk_fma_f32 v[232:233], v[86:87], v[232:233], v[236:237]
	v_cvt_pk_bf16_f32 v230, v230, v231
	v_cvt_pk_bf16_f32 v231, v232, v233
	v_lshlrev_b32_e32 v194, 16, v196
	v_and_b32_e32 v195, 0xffff0000, v196
	v_lshlrev_b32_e32 v198, 16, v197
	v_and_b32_e32 v199, 0xffff0000, v197
	v_lshlrev_b32_e32 v234, 16, v200
	v_and_b32_e32 v235, 0xffff0000, v200
	v_lshlrev_b32_e32 v236, 16, v201
	v_and_b32_e32 v237, 0xffff0000, v201
	v_pk_fma_f32 v[194:195], v[80:81], v[194:195], v[234:235]
	v_pk_fma_f32 v[198:199], v[82:83], v[198:199], v[236:237]
	v_cvt_pk_bf16_f32 v232, v194, v195
	v_cvt_pk_bf16_f32 v233, v198, v199
	v_add_co_u32_e32 v236, vcc, 0x10100, v246
	v_addc_co_u32_e32 v237, vcc, 0, v247, vcc
	global_store_dwordx2 v[236:237], v[230:231], off
	global_store_dwordx2 v[236:237], v[232:233], off offset:32
	v_add_co_u32_e32 v236, vcc, 0x18000, v244
	v_addc_co_u32_e32 v237, vcc, 0, v245, vcc
	global_load_dwordx2 v[194:195], v[236:237], off
	global_load_dwordx2 v[196:197], v[236:237], off offset:32
	v_add_co_u32_e32 v236, vcc, 0x18000, v246
	v_addc_co_u32_e32 v237, vcc, 0, v247, vcc
	global_load_dwordx2 v[198:199], v[236:237], off
	global_load_dwordx2 v[200:201], v[236:237], off offset:32
	s_waitcnt vmcnt(0)
	v_lshlrev_b32_e32 v230, 16, v194
	v_and_b32_e32 v231, 0xffff0000, v194
	v_lshlrev_b32_e32 v232, 16, v195
	v_and_b32_e32 v233, 0xffff0000, v195
	v_lshlrev_b32_e32 v234, 16, v198
	v_and_b32_e32 v235, 0xffff0000, v198
	v_lshlrev_b32_e32 v236, 16, v199
	v_and_b32_e32 v237, 0xffff0000, v199
	v_pk_fma_f32 v[230:231], v[76:77], v[230:231], v[234:235]
	v_pk_fma_f32 v[232:233], v[78:79], v[232:233], v[236:237]
	v_cvt_pk_bf16_f32 v230, v230, v231
	v_cvt_pk_bf16_f32 v231, v232, v233
	v_lshlrev_b32_e32 v194, 16, v196
	v_and_b32_e32 v195, 0xffff0000, v196
	v_lshlrev_b32_e32 v198, 16, v197
	v_and_b32_e32 v199, 0xffff0000, v197
	v_lshlrev_b32_e32 v234, 16, v200
	v_and_b32_e32 v235, 0xffff0000, v200
	v_lshlrev_b32_e32 v236, 16, v201
	v_and_b32_e32 v237, 0xffff0000, v201
	v_pk_fma_f32 v[194:195], v[72:73], v[194:195], v[234:235]
	v_pk_fma_f32 v[198:199], v[74:75], v[198:199], v[236:237]
	v_cvt_pk_bf16_f32 v232, v194, v195
	v_cvt_pk_bf16_f32 v233, v198, v199
	v_add_co_u32_e32 v236, vcc, 0x18000, v246
	v_addc_co_u32_e32 v237, vcc, 0, v247, vcc
	global_store_dwordx2 v[236:237], v[230:231], off
	global_store_dwordx2 v[236:237], v[232:233], off offset:32
	v_add_co_u32_e32 v236, vcc, 0x18100, v244
	v_addc_co_u32_e32 v237, vcc, 0, v245, vcc
	global_load_dwordx2 v[194:195], v[236:237], off
	global_load_dwordx2 v[196:197], v[236:237], off offset:32
	v_add_co_u32_e32 v236, vcc, 0x18100, v246
	v_addc_co_u32_e32 v237, vcc, 0, v247, vcc
	global_load_dwordx2 v[198:199], v[236:237], off
	global_load_dwordx2 v[200:201], v[236:237], off offset:32
	s_waitcnt vmcnt(0)
	v_lshlrev_b32_e32 v230, 16, v194
	v_and_b32_e32 v231, 0xffff0000, v194
	v_lshlrev_b32_e32 v232, 16, v195
	v_and_b32_e32 v233, 0xffff0000, v195
	v_lshlrev_b32_e32 v234, 16, v198
	v_and_b32_e32 v235, 0xffff0000, v198
	v_lshlrev_b32_e32 v236, 16, v199
	v_and_b32_e32 v237, 0xffff0000, v199
	v_pk_fma_f32 v[230:231], v[68:69], v[230:231], v[234:235]
	v_pk_fma_f32 v[232:233], v[70:71], v[232:233], v[236:237]
	v_cvt_pk_bf16_f32 v230, v230, v231
	v_cvt_pk_bf16_f32 v231, v232, v233
	v_lshlrev_b32_e32 v194, 16, v196
	v_and_b32_e32 v195, 0xffff0000, v196
	v_lshlrev_b32_e32 v198, 16, v197
	v_and_b32_e32 v199, 0xffff0000, v197
	v_lshlrev_b32_e32 v234, 16, v200
	v_and_b32_e32 v235, 0xffff0000, v200
	v_lshlrev_b32_e32 v236, 16, v201
	v_and_b32_e32 v237, 0xffff0000, v201
	v_pk_fma_f32 v[194:195], v[64:65], v[194:195], v[234:235]
	v_pk_fma_f32 v[198:199], v[66:67], v[198:199], v[236:237]
	v_cvt_pk_bf16_f32 v232, v194, v195
	v_cvt_pk_bf16_f32 v233, v198, v199
	v_add_co_u32_e32 v236, vcc, 0x18100, v246
	v_addc_co_u32_e32 v237, vcc, 0, v247, vcc
	global_store_dwordx2 v[236:237], v[230:231], off
	global_store_dwordx2 v[236:237], v[232:233], off offset:32
	v_add_co_u32_e32 v236, vcc, 0x40000, v244
	v_addc_co_u32_e32 v237, vcc, 0, v245, vcc
	global_load_dwordx2 v[194:195], v[236:237], off
	global_load_dwordx2 v[196:197], v[236:237], off offset:32
	v_add_co_u32_e32 v236, vcc, 0x40000, v246
	v_addc_co_u32_e32 v237, vcc, 0, v247, vcc
	global_load_dwordx2 v[198:199], v[236:237], off
	global_load_dwordx2 v[200:201], v[236:237], off offset:32
	s_waitcnt vmcnt(0)
	v_lshlrev_b32_e32 v230, 16, v194
	v_and_b32_e32 v231, 0xffff0000, v194
	v_lshlrev_b32_e32 v232, 16, v195
	v_and_b32_e32 v233, 0xffff0000, v195
	v_lshlrev_b32_e32 v234, 16, v198
	v_and_b32_e32 v235, 0xffff0000, v198
	v_lshlrev_b32_e32 v236, 16, v199
	v_and_b32_e32 v237, 0xffff0000, v199
	v_pk_fma_f32 v[230:231], v[60:61], v[230:231], v[234:235]
	v_pk_fma_f32 v[232:233], v[62:63], v[232:233], v[236:237]
	v_cvt_pk_bf16_f32 v230, v230, v231
	v_cvt_pk_bf16_f32 v231, v232, v233
	v_lshlrev_b32_e32 v194, 16, v196
	v_and_b32_e32 v195, 0xffff0000, v196
	v_lshlrev_b32_e32 v198, 16, v197
	v_and_b32_e32 v199, 0xffff0000, v197
	v_lshlrev_b32_e32 v234, 16, v200
	v_and_b32_e32 v235, 0xffff0000, v200
	v_lshlrev_b32_e32 v236, 16, v201
	v_and_b32_e32 v237, 0xffff0000, v201
	v_pk_fma_f32 v[194:195], v[56:57], v[194:195], v[234:235]
	v_pk_fma_f32 v[198:199], v[58:59], v[198:199], v[236:237]
	v_cvt_pk_bf16_f32 v232, v194, v195
	v_cvt_pk_bf16_f32 v233, v198, v199
	v_add_co_u32_e32 v236, vcc, 0x40000, v246
	v_addc_co_u32_e32 v237, vcc, 0, v247, vcc
	global_store_dwordx2 v[236:237], v[230:231], off
	global_store_dwordx2 v[236:237], v[232:233], off offset:32
	v_add_co_u32_e32 v236, vcc, 0x40100, v244
	v_addc_co_u32_e32 v237, vcc, 0, v245, vcc
	global_load_dwordx2 v[194:195], v[236:237], off
	global_load_dwordx2 v[196:197], v[236:237], off offset:32
	v_add_co_u32_e32 v236, vcc, 0x40100, v246
	v_addc_co_u32_e32 v237, vcc, 0, v247, vcc
	global_load_dwordx2 v[198:199], v[236:237], off
	global_load_dwordx2 v[200:201], v[236:237], off offset:32
	s_waitcnt vmcnt(0)
	v_lshlrev_b32_e32 v230, 16, v194
	v_and_b32_e32 v231, 0xffff0000, v194
	v_lshlrev_b32_e32 v232, 16, v195
	v_and_b32_e32 v233, 0xffff0000, v195
	v_lshlrev_b32_e32 v234, 16, v198
	v_and_b32_e32 v235, 0xffff0000, v198
	v_lshlrev_b32_e32 v236, 16, v199
	v_and_b32_e32 v237, 0xffff0000, v199
	v_pk_fma_f32 v[230:231], v[52:53], v[230:231], v[234:235]
	v_pk_fma_f32 v[232:233], v[54:55], v[232:233], v[236:237]
	v_cvt_pk_bf16_f32 v230, v230, v231
	v_cvt_pk_bf16_f32 v231, v232, v233
	v_lshlrev_b32_e32 v194, 16, v196
	v_and_b32_e32 v195, 0xffff0000, v196
	v_lshlrev_b32_e32 v198, 16, v197
	v_and_b32_e32 v199, 0xffff0000, v197
	v_lshlrev_b32_e32 v234, 16, v200
	v_and_b32_e32 v235, 0xffff0000, v200
	v_lshlrev_b32_e32 v236, 16, v201
	v_and_b32_e32 v237, 0xffff0000, v201
	v_pk_fma_f32 v[194:195], v[48:49], v[194:195], v[234:235]
	v_pk_fma_f32 v[198:199], v[50:51], v[198:199], v[236:237]
	v_cvt_pk_bf16_f32 v232, v194, v195
	v_cvt_pk_bf16_f32 v233, v198, v199
	v_add_co_u32_e32 v236, vcc, 0x40100, v246
	v_addc_co_u32_e32 v237, vcc, 0, v247, vcc
	global_store_dwordx2 v[236:237], v[230:231], off
	global_store_dwordx2 v[236:237], v[232:233], off offset:32
	v_add_co_u32_e32 v236, vcc, 0x48000, v244
	v_addc_co_u32_e32 v237, vcc, 0, v245, vcc
	global_load_dwordx2 v[194:195], v[236:237], off
	global_load_dwordx2 v[196:197], v[236:237], off offset:32
	v_add_co_u32_e32 v236, vcc, 0x48000, v246
	v_addc_co_u32_e32 v237, vcc, 0, v247, vcc
	global_load_dwordx2 v[198:199], v[236:237], off
	global_load_dwordx2 v[200:201], v[236:237], off offset:32
	s_waitcnt vmcnt(0)
	v_lshlrev_b32_e32 v230, 16, v194
	v_and_b32_e32 v231, 0xffff0000, v194
	v_lshlrev_b32_e32 v232, 16, v195
	v_and_b32_e32 v233, 0xffff0000, v195
	v_lshlrev_b32_e32 v234, 16, v198
	v_and_b32_e32 v235, 0xffff0000, v198
	v_lshlrev_b32_e32 v236, 16, v199
	v_and_b32_e32 v237, 0xffff0000, v199
	v_pk_fma_f32 v[230:231], v[44:45], v[230:231], v[234:235]
	v_pk_fma_f32 v[232:233], v[46:47], v[232:233], v[236:237]
	v_cvt_pk_bf16_f32 v230, v230, v231
	v_cvt_pk_bf16_f32 v231, v232, v233
	v_lshlrev_b32_e32 v194, 16, v196
	v_and_b32_e32 v195, 0xffff0000, v196
	v_lshlrev_b32_e32 v198, 16, v197
	v_and_b32_e32 v199, 0xffff0000, v197
	v_lshlrev_b32_e32 v234, 16, v200
	v_and_b32_e32 v235, 0xffff0000, v200
	v_lshlrev_b32_e32 v236, 16, v201
	v_and_b32_e32 v237, 0xffff0000, v201
	v_pk_fma_f32 v[194:195], v[40:41], v[194:195], v[234:235]
	v_pk_fma_f32 v[198:199], v[42:43], v[198:199], v[236:237]
	v_cvt_pk_bf16_f32 v232, v194, v195
	v_cvt_pk_bf16_f32 v233, v198, v199
	v_add_co_u32_e32 v236, vcc, 0x48000, v246
	v_addc_co_u32_e32 v237, vcc, 0, v247, vcc
	global_store_dwordx2 v[236:237], v[230:231], off
	global_store_dwordx2 v[236:237], v[232:233], off offset:32
	v_add_co_u32_e32 v236, vcc, 0x48100, v244
	v_addc_co_u32_e32 v237, vcc, 0, v245, vcc
	global_load_dwordx2 v[194:195], v[236:237], off
	global_load_dwordx2 v[196:197], v[236:237], off offset:32
	v_add_co_u32_e32 v236, vcc, 0x48100, v246
	v_addc_co_u32_e32 v237, vcc, 0, v247, vcc
	global_load_dwordx2 v[198:199], v[236:237], off
	global_load_dwordx2 v[200:201], v[236:237], off offset:32
	s_waitcnt vmcnt(0)
	v_lshlrev_b32_e32 v230, 16, v194
	v_and_b32_e32 v231, 0xffff0000, v194
	v_lshlrev_b32_e32 v232, 16, v195
	v_and_b32_e32 v233, 0xffff0000, v195
	v_lshlrev_b32_e32 v234, 16, v198
	v_and_b32_e32 v235, 0xffff0000, v198
	v_lshlrev_b32_e32 v236, 16, v199
	v_and_b32_e32 v237, 0xffff0000, v199
	v_pk_fma_f32 v[230:231], v[36:37], v[230:231], v[234:235]
	v_pk_fma_f32 v[232:233], v[38:39], v[232:233], v[236:237]
	v_cvt_pk_bf16_f32 v230, v230, v231
	v_cvt_pk_bf16_f32 v231, v232, v233
	v_lshlrev_b32_e32 v194, 16, v196
	v_and_b32_e32 v195, 0xffff0000, v196
	v_lshlrev_b32_e32 v198, 16, v197
	v_and_b32_e32 v199, 0xffff0000, v197
	v_lshlrev_b32_e32 v234, 16, v200
	v_and_b32_e32 v235, 0xffff0000, v200
	v_lshlrev_b32_e32 v236, 16, v201
	v_and_b32_e32 v237, 0xffff0000, v201
	v_pk_fma_f32 v[194:195], v[32:33], v[194:195], v[234:235]
	v_pk_fma_f32 v[198:199], v[34:35], v[198:199], v[236:237]
	v_cvt_pk_bf16_f32 v232, v194, v195
	v_cvt_pk_bf16_f32 v233, v198, v199
	v_add_co_u32_e32 v236, vcc, 0x48100, v246
	v_addc_co_u32_e32 v237, vcc, 0, v247, vcc
	global_store_dwordx2 v[236:237], v[230:231], off
	global_store_dwordx2 v[236:237], v[232:233], off offset:32
	v_add_co_u32_e32 v236, vcc, 0x50000, v244
	v_addc_co_u32_e32 v237, vcc, 0, v245, vcc
	global_load_dwordx2 v[194:195], v[236:237], off
	global_load_dwordx2 v[196:197], v[236:237], off offset:32
	v_add_co_u32_e32 v236, vcc, 0x50000, v246
	v_addc_co_u32_e32 v237, vcc, 0, v247, vcc
	global_load_dwordx2 v[198:199], v[236:237], off
	global_load_dwordx2 v[200:201], v[236:237], off offset:32
	s_waitcnt vmcnt(0)
	v_lshlrev_b32_e32 v230, 16, v194
	v_and_b32_e32 v231, 0xffff0000, v194
	v_lshlrev_b32_e32 v232, 16, v195
	v_and_b32_e32 v233, 0xffff0000, v195
	v_lshlrev_b32_e32 v234, 16, v198
	v_and_b32_e32 v235, 0xffff0000, v198
	v_lshlrev_b32_e32 v236, 16, v199
	v_and_b32_e32 v237, 0xffff0000, v199
	v_pk_fma_f32 v[230:231], v[28:29], v[230:231], v[234:235]
	v_pk_fma_f32 v[232:233], v[30:31], v[232:233], v[236:237]
	v_cvt_pk_bf16_f32 v230, v230, v231
	v_cvt_pk_bf16_f32 v231, v232, v233
	v_lshlrev_b32_e32 v194, 16, v196
	v_and_b32_e32 v195, 0xffff0000, v196
	v_lshlrev_b32_e32 v198, 16, v197
	v_and_b32_e32 v199, 0xffff0000, v197
	v_lshlrev_b32_e32 v234, 16, v200
	v_and_b32_e32 v235, 0xffff0000, v200
	v_lshlrev_b32_e32 v236, 16, v201
	v_and_b32_e32 v237, 0xffff0000, v201
	v_pk_fma_f32 v[194:195], v[24:25], v[194:195], v[234:235]
	v_pk_fma_f32 v[198:199], v[26:27], v[198:199], v[236:237]
	v_cvt_pk_bf16_f32 v232, v194, v195
	v_cvt_pk_bf16_f32 v233, v198, v199
	v_add_co_u32_e32 v236, vcc, 0x50000, v246
	v_addc_co_u32_e32 v237, vcc, 0, v247, vcc
	global_store_dwordx2 v[236:237], v[230:231], off
	global_store_dwordx2 v[236:237], v[232:233], off offset:32
	v_add_co_u32_e32 v236, vcc, 0x50100, v244
	v_addc_co_u32_e32 v237, vcc, 0, v245, vcc
	global_load_dwordx2 v[194:195], v[236:237], off
	global_load_dwordx2 v[196:197], v[236:237], off offset:32
	v_add_co_u32_e32 v236, vcc, 0x50100, v246
	v_addc_co_u32_e32 v237, vcc, 0, v247, vcc
	global_load_dwordx2 v[198:199], v[236:237], off
	global_load_dwordx2 v[200:201], v[236:237], off offset:32
	s_waitcnt vmcnt(0)
	v_lshlrev_b32_e32 v230, 16, v194
	v_and_b32_e32 v231, 0xffff0000, v194
	v_lshlrev_b32_e32 v232, 16, v195
	v_and_b32_e32 v233, 0xffff0000, v195
	v_lshlrev_b32_e32 v234, 16, v198
	v_and_b32_e32 v235, 0xffff0000, v198
	v_lshlrev_b32_e32 v236, 16, v199
	v_and_b32_e32 v237, 0xffff0000, v199
	v_pk_fma_f32 v[230:231], v[20:21], v[230:231], v[234:235]
	v_pk_fma_f32 v[232:233], v[22:23], v[232:233], v[236:237]
	v_cvt_pk_bf16_f32 v230, v230, v231
	v_cvt_pk_bf16_f32 v231, v232, v233
	v_lshlrev_b32_e32 v194, 16, v196
	v_and_b32_e32 v195, 0xffff0000, v196
	v_lshlrev_b32_e32 v198, 16, v197
	v_and_b32_e32 v199, 0xffff0000, v197
	v_lshlrev_b32_e32 v234, 16, v200
	v_and_b32_e32 v235, 0xffff0000, v200
	v_lshlrev_b32_e32 v236, 16, v201
	v_and_b32_e32 v237, 0xffff0000, v201
	v_pk_fma_f32 v[194:195], v[16:17], v[194:195], v[234:235]
	v_pk_fma_f32 v[198:199], v[18:19], v[198:199], v[236:237]
	v_cvt_pk_bf16_f32 v232, v194, v195
	v_cvt_pk_bf16_f32 v233, v198, v199
	v_add_co_u32_e32 v236, vcc, 0x50100, v246
	v_addc_co_u32_e32 v237, vcc, 0, v247, vcc
	global_store_dwordx2 v[236:237], v[230:231], off
	global_store_dwordx2 v[236:237], v[232:233], off offset:32
	v_add_co_u32_e32 v236, vcc, 0x58000, v244
	v_addc_co_u32_e32 v237, vcc, 0, v245, vcc
	global_load_dwordx2 v[194:195], v[236:237], off
	global_load_dwordx2 v[196:197], v[236:237], off offset:32
	v_add_co_u32_e32 v236, vcc, 0x58000, v246
	v_addc_co_u32_e32 v237, vcc, 0, v247, vcc
	global_load_dwordx2 v[198:199], v[236:237], off
	global_load_dwordx2 v[200:201], v[236:237], off offset:32
	s_waitcnt vmcnt(0)
	v_lshlrev_b32_e32 v230, 16, v194
	v_and_b32_e32 v231, 0xffff0000, v194
	v_lshlrev_b32_e32 v232, 16, v195
	v_and_b32_e32 v233, 0xffff0000, v195
	v_lshlrev_b32_e32 v234, 16, v198
	v_and_b32_e32 v235, 0xffff0000, v198
	v_lshlrev_b32_e32 v236, 16, v199
	v_and_b32_e32 v237, 0xffff0000, v199
	v_pk_fma_f32 v[230:231], v[12:13], v[230:231], v[234:235]
	v_pk_fma_f32 v[232:233], v[14:15], v[232:233], v[236:237]
	v_cvt_pk_bf16_f32 v230, v230, v231
	v_cvt_pk_bf16_f32 v231, v232, v233
	v_lshlrev_b32_e32 v194, 16, v196
	v_and_b32_e32 v195, 0xffff0000, v196
	v_lshlrev_b32_e32 v198, 16, v197
	v_and_b32_e32 v199, 0xffff0000, v197
	v_lshlrev_b32_e32 v234, 16, v200
	v_and_b32_e32 v235, 0xffff0000, v200
	v_lshlrev_b32_e32 v236, 16, v201
	v_and_b32_e32 v237, 0xffff0000, v201
	v_pk_fma_f32 v[194:195], v[8:9], v[194:195], v[234:235]
	v_pk_fma_f32 v[198:199], v[10:11], v[198:199], v[236:237]
	v_cvt_pk_bf16_f32 v232, v194, v195
	v_cvt_pk_bf16_f32 v233, v198, v199
	v_add_co_u32_e32 v236, vcc, 0x58000, v246
	v_addc_co_u32_e32 v237, vcc, 0, v247, vcc
	global_store_dwordx2 v[236:237], v[230:231], off
	global_store_dwordx2 v[236:237], v[232:233], off offset:32
	v_add_co_u32_e32 v236, vcc, 0x58100, v244
	v_addc_co_u32_e32 v237, vcc, 0, v245, vcc
	global_load_dwordx2 v[194:195], v[236:237], off
	global_load_dwordx2 v[196:197], v[236:237], off offset:32
	v_add_co_u32_e32 v236, vcc, 0x58100, v246
	v_addc_co_u32_e32 v237, vcc, 0, v247, vcc
	global_load_dwordx2 v[198:199], v[236:237], off
	global_load_dwordx2 v[200:201], v[236:237], off offset:32
	s_waitcnt vmcnt(0)
	v_lshlrev_b32_e32 v230, 16, v194
	v_and_b32_e32 v231, 0xffff0000, v194
	v_lshlrev_b32_e32 v232, 16, v195
	v_and_b32_e32 v233, 0xffff0000, v195
	v_lshlrev_b32_e32 v234, 16, v198
	v_and_b32_e32 v235, 0xffff0000, v198
	v_lshlrev_b32_e32 v236, 16, v199
	v_and_b32_e32 v237, 0xffff0000, v199
	v_pk_fma_f32 v[230:231], v[4:5], v[230:231], v[234:235]
	v_pk_fma_f32 v[232:233], v[6:7], v[232:233], v[236:237]
	v_cvt_pk_bf16_f32 v230, v230, v231
	v_cvt_pk_bf16_f32 v231, v232, v233
	v_lshlrev_b32_e32 v194, 16, v196
	v_and_b32_e32 v195, 0xffff0000, v196
	v_lshlrev_b32_e32 v198, 16, v197
	v_and_b32_e32 v199, 0xffff0000, v197
	v_lshlrev_b32_e32 v234, 16, v200
	v_and_b32_e32 v235, 0xffff0000, v200
	v_lshlrev_b32_e32 v236, 16, v201
	v_and_b32_e32 v237, 0xffff0000, v201
	v_pk_fma_f32 v[194:195], v[0:1], v[194:195], v[234:235]
	v_pk_fma_f32 v[198:199], v[2:3], v[198:199], v[236:237]
	v_cvt_pk_bf16_f32 v232, v194, v195
	v_cvt_pk_bf16_f32 v233, v198, v199
	v_add_co_u32_e32 v236, vcc, 0x58100, v246
	v_addc_co_u32_e32 v237, vcc, 0, v247, vcc
	global_store_dwordx2 v[236:237], v[230:231], off
	global_store_dwordx2 v[236:237], v[232:233], off offset:32
	s_branch .LBB0_1065
.Lfb_k0:
	v_mov_b32_e32 v236, v244
	v_mov_b32_e32 v237, v245
	global_load_dwordx2 v[194:195], v[236:237], off
	global_load_dwordx2 v[196:197], v[236:237], off offset:32
	s_waitcnt vmcnt(0)
	v_lshlrev_b32_e32 v230, 16, v194
	v_and_b32_e32 v231, 0xffff0000, v194
	v_lshlrev_b32_e32 v232, 16, v195
	v_and_b32_e32 v233, 0xffff0000, v195
	v_pk_mul_f32 v[230:231], v[124:125], v[230:231]
	v_pk_mul_f32 v[232:233], v[126:127], v[232:233]
	v_cvt_pk_bf16_f32 v230, v230, v231
	v_cvt_pk_bf16_f32 v231, v232, v233
	v_lshlrev_b32_e32 v234, 16, v196
	v_and_b32_e32 v235, 0xffff0000, v196
	v_lshlrev_b32_e32 v236, 16, v197
	v_and_b32_e32 v237, 0xffff0000, v197
	v_pk_mul_f32 v[234:235], v[120:121], v[234:235]
	v_pk_mul_f32 v[236:237], v[122:123], v[236:237]
	v_cvt_pk_bf16_f32 v232, v234, v235
	v_cvt_pk_bf16_f32 v233, v236, v237
	v_mov_b32_e32 v236, v246
	v_mov_b32_e32 v237, v247
	global_store_dwordx2 v[236:237], v[230:231], off
	global_store_dwordx2 v[236:237], v[232:233], off offset:32
	v_add_co_u32_e32 v236, vcc, 0x100, v244
	v_addc_co_u32_e32 v237, vcc, 0, v245, vcc
	global_load_dwordx2 v[194:195], v[236:237], off
	global_load_dwordx2 v[196:197], v[236:237], off offset:32
	s_waitcnt vmcnt(0)
	v_lshlrev_b32_e32 v230, 16, v194
	v_and_b32_e32 v231, 0xffff0000, v194
	v_lshlrev_b32_e32 v232, 16, v195
	v_and_b32_e32 v233, 0xffff0000, v195
	v_pk_mul_f32 v[230:231], v[116:117], v[230:231]
	v_pk_mul_f32 v[232:233], v[118:119], v[232:233]
	v_cvt_pk_bf16_f32 v230, v230, v231
	v_cvt_pk_bf16_f32 v231, v232, v233
	v_lshlrev_b32_e32 v234, 16, v196
	v_and_b32_e32 v235, 0xffff0000, v196
	v_lshlrev_b32_e32 v236, 16, v197
	v_and_b32_e32 v237, 0xffff0000, v197
	v_pk_mul_f32 v[234:235], v[112:113], v[234:235]
	v_pk_mul_f32 v[236:237], v[114:115], v[236:237]
	v_cvt_pk_bf16_f32 v232, v234, v235
	v_cvt_pk_bf16_f32 v233, v236, v237
	v_add_co_u32_e32 v236, vcc, 0x100, v246
	v_addc_co_u32_e32 v237, vcc, 0, v247, vcc
	global_store_dwordx2 v[236:237], v[230:231], off
	global_store_dwordx2 v[236:237], v[232:233], off offset:32
	v_add_co_u32_e32 v236, vcc, 0x8000, v244
	v_addc_co_u32_e32 v237, vcc, 0, v245, vcc
	global_load_dwordx2 v[194:195], v[236:237], off
	global_load_dwordx2 v[196:197], v[236:237], off offset:32
	s_waitcnt vmcnt(0)
	v_lshlrev_b32_e32 v230, 16, v194
	v_and_b32_e32 v231, 0xffff0000, v194
	v_lshlrev_b32_e32 v232, 16, v195
	v_and_b32_e32 v233, 0xffff0000, v195
	v_pk_mul_f32 v[230:231], v[108:109], v[230:231]
	v_pk_mul_f32 v[232:233], v[110:111], v[232:233]
	v_cvt_pk_bf16_f32 v230, v230, v231
	v_cvt_pk_bf16_f32 v231, v232, v233
	v_lshlrev_b32_e32 v234, 16, v196
	v_and_b32_e32 v235, 0xffff0000, v196
	v_lshlrev_b32_e32 v236, 16, v197
	v_and_b32_e32 v237, 0xffff0000, v197
	v_pk_mul_f32 v[234:235], v[104:105], v[234:235]
	v_pk_mul_f32 v[236:237], v[106:107], v[236:237]
	v_cvt_pk_bf16_f32 v232, v234, v235
	v_cvt_pk_bf16_f32 v233, v236, v237
	v_add_co_u32_e32 v236, vcc, 0x8000, v246
	v_addc_co_u32_e32 v237, vcc, 0, v247, vcc
	global_store_dwordx2 v[236:237], v[230:231], off
	global_store_dwordx2 v[236:237], v[232:233], off offset:32
	v_add_co_u32_e32 v236, vcc, 0x8100, v244
	v_addc_co_u32_e32 v237, vcc, 0, v245, vcc
	global_load_dwordx2 v[194:195], v[236:237], off
	global_load_dwordx2 v[196:197], v[236:237], off offset:32
	s_waitcnt vmcnt(0)
	v_lshlrev_b32_e32 v230, 16, v194
	v_and_b32_e32 v231, 0xffff0000, v194
	v_lshlrev_b32_e32 v232, 16, v195
	v_and_b32_e32 v233, 0xffff0000, v195
	v_pk_mul_f32 v[230:231], v[100:101], v[230:231]
	v_pk_mul_f32 v[232:233], v[102:103], v[232:233]
	v_cvt_pk_bf16_f32 v230, v230, v231
	v_cvt_pk_bf16_f32 v231, v232, v233
	v_lshlrev_b32_e32 v234, 16, v196
	v_and_b32_e32 v235, 0xffff0000, v196
	v_lshlrev_b32_e32 v236, 16, v197
	v_and_b32_e32 v237, 0xffff0000, v197
	v_pk_mul_f32 v[234:235], v[96:97], v[234:235]
	v_pk_mul_f32 v[236:237], v[98:99], v[236:237]
	v_cvt_pk_bf16_f32 v232, v234, v235
	v_cvt_pk_bf16_f32 v233, v236, v237
	v_add_co_u32_e32 v236, vcc, 0x8100, v246
	v_addc_co_u32_e32 v237, vcc, 0, v247, vcc
	global_store_dwordx2 v[236:237], v[230:231], off
	global_store_dwordx2 v[236:237], v[232:233], off offset:32
	v_add_co_u32_e32 v236, vcc, 0x10000, v244
	v_addc_co_u32_e32 v237, vcc, 0, v245, vcc
	global_load_dwordx2 v[194:195], v[236:237], off
	global_load_dwordx2 v[196:197], v[236:237], off offset:32
	s_waitcnt vmcnt(0)
	v_lshlrev_b32_e32 v230, 16, v194
	v_and_b32_e32 v231, 0xffff0000, v194
	v_lshlrev_b32_e32 v232, 16, v195
	v_and_b32_e32 v233, 0xffff0000, v195
	v_pk_mul_f32 v[230:231], v[92:93], v[230:231]
	v_pk_mul_f32 v[232:233], v[94:95], v[232:233]
	v_cvt_pk_bf16_f32 v230, v230, v231
	v_cvt_pk_bf16_f32 v231, v232, v233
	v_lshlrev_b32_e32 v234, 16, v196
	v_and_b32_e32 v235, 0xffff0000, v196
	v_lshlrev_b32_e32 v236, 16, v197
	v_and_b32_e32 v237, 0xffff0000, v197
	v_pk_mul_f32 v[234:235], v[88:89], v[234:235]
	v_pk_mul_f32 v[236:237], v[90:91], v[236:237]
	v_cvt_pk_bf16_f32 v232, v234, v235
	v_cvt_pk_bf16_f32 v233, v236, v237
	v_add_co_u32_e32 v236, vcc, 0x10000, v246
	v_addc_co_u32_e32 v237, vcc, 0, v247, vcc
	global_store_dwordx2 v[236:237], v[230:231], off
	global_store_dwordx2 v[236:237], v[232:233], off offset:32
	v_add_co_u32_e32 v236, vcc, 0x10100, v244
	v_addc_co_u32_e32 v237, vcc, 0, v245, vcc
	global_load_dwordx2 v[194:195], v[236:237], off
	global_load_dwordx2 v[196:197], v[236:237], off offset:32
	s_waitcnt vmcnt(0)
	v_lshlrev_b32_e32 v230, 16, v194
	v_and_b32_e32 v231, 0xffff0000, v194
	v_lshlrev_b32_e32 v232, 16, v195
	v_and_b32_e32 v233, 0xffff0000, v195
	v_pk_mul_f32 v[230:231], v[84:85], v[230:231]
	v_pk_mul_f32 v[232:233], v[86:87], v[232:233]
	v_cvt_pk_bf16_f32 v230, v230, v231
	v_cvt_pk_bf16_f32 v231, v232, v233
	v_lshlrev_b32_e32 v234, 16, v196
	v_and_b32_e32 v235, 0xffff0000, v196
	v_lshlrev_b32_e32 v236, 16, v197
	v_and_b32_e32 v237, 0xffff0000, v197
	v_pk_mul_f32 v[234:235], v[80:81], v[234:235]
	v_pk_mul_f32 v[236:237], v[82:83], v[236:237]
	v_cvt_pk_bf16_f32 v232, v234, v235
	v_cvt_pk_bf16_f32 v233, v236, v237
	v_add_co_u32_e32 v236, vcc, 0x10100, v246
	v_addc_co_u32_e32 v237, vcc, 0, v247, vcc
	global_store_dwordx2 v[236:237], v[230:231], off
	global_store_dwordx2 v[236:237], v[232:233], off offset:32
	v_add_co_u32_e32 v236, vcc, 0x18000, v244
	v_addc_co_u32_e32 v237, vcc, 0, v245, vcc
	global_load_dwordx2 v[194:195], v[236:237], off
	global_load_dwordx2 v[196:197], v[236:237], off offset:32
	s_waitcnt vmcnt(0)
	v_lshlrev_b32_e32 v230, 16, v194
	v_and_b32_e32 v231, 0xffff0000, v194
	v_lshlrev_b32_e32 v232, 16, v195
	v_and_b32_e32 v233, 0xffff0000, v195
	v_pk_mul_f32 v[230:231], v[76:77], v[230:231]
	v_pk_mul_f32 v[232:233], v[78:79], v[232:233]
	v_cvt_pk_bf16_f32 v230, v230, v231
	v_cvt_pk_bf16_f32 v231, v232, v233
	v_lshlrev_b32_e32 v234, 16, v196
	v_and_b32_e32 v235, 0xffff0000, v196
	v_lshlrev_b32_e32 v236, 16, v197
	v_and_b32_e32 v237, 0xffff0000, v197
	v_pk_mul_f32 v[234:235], v[72:73], v[234:235]
	v_pk_mul_f32 v[236:237], v[74:75], v[236:237]
	v_cvt_pk_bf16_f32 v232, v234, v235
	v_cvt_pk_bf16_f32 v233, v236, v237
	v_add_co_u32_e32 v236, vcc, 0x18000, v246
	v_addc_co_u32_e32 v237, vcc, 0, v247, vcc
	global_store_dwordx2 v[236:237], v[230:231], off
	global_store_dwordx2 v[236:237], v[232:233], off offset:32
	v_add_co_u32_e32 v236, vcc, 0x18100, v244
	v_addc_co_u32_e32 v237, vcc, 0, v245, vcc
	global_load_dwordx2 v[194:195], v[236:237], off
	global_load_dwordx2 v[196:197], v[236:237], off offset:32
	s_waitcnt vmcnt(0)
	v_lshlrev_b32_e32 v230, 16, v194
	v_and_b32_e32 v231, 0xffff0000, v194
	v_lshlrev_b32_e32 v232, 16, v195
	v_and_b32_e32 v233, 0xffff0000, v195
	v_pk_mul_f32 v[230:231], v[68:69], v[230:231]
	v_pk_mul_f32 v[232:233], v[70:71], v[232:233]
	v_cvt_pk_bf16_f32 v230, v230, v231
	v_cvt_pk_bf16_f32 v231, v232, v233
	v_lshlrev_b32_e32 v234, 16, v196
	v_and_b32_e32 v235, 0xffff0000, v196
	v_lshlrev_b32_e32 v236, 16, v197
	v_and_b32_e32 v237, 0xffff0000, v197
	v_pk_mul_f32 v[234:235], v[64:65], v[234:235]
	v_pk_mul_f32 v[236:237], v[66:67], v[236:237]
	v_cvt_pk_bf16_f32 v232, v234, v235
	v_cvt_pk_bf16_f32 v233, v236, v237
	v_add_co_u32_e32 v236, vcc, 0x18100, v246
	v_addc_co_u32_e32 v237, vcc, 0, v247, vcc
	global_store_dwordx2 v[236:237], v[230:231], off
	global_store_dwordx2 v[236:237], v[232:233], off offset:32
	v_add_co_u32_e32 v236, vcc, 0x40000, v244
	v_addc_co_u32_e32 v237, vcc, 0, v245, vcc
	global_load_dwordx2 v[194:195], v[236:237], off
	global_load_dwordx2 v[196:197], v[236:237], off offset:32
	s_waitcnt vmcnt(0)
	v_lshlrev_b32_e32 v230, 16, v194
	v_and_b32_e32 v231, 0xffff0000, v194
	v_lshlrev_b32_e32 v232, 16, v195
	v_and_b32_e32 v233, 0xffff0000, v195
	v_pk_mul_f32 v[230:231], v[60:61], v[230:231]
	v_pk_mul_f32 v[232:233], v[62:63], v[232:233]
	v_cvt_pk_bf16_f32 v230, v230, v231
	v_cvt_pk_bf16_f32 v231, v232, v233
	v_lshlrev_b32_e32 v234, 16, v196
	v_and_b32_e32 v235, 0xffff0000, v196
	v_lshlrev_b32_e32 v236, 16, v197
	v_and_b32_e32 v237, 0xffff0000, v197
	v_pk_mul_f32 v[234:235], v[56:57], v[234:235]
	v_pk_mul_f32 v[236:237], v[58:59], v[236:237]
	v_cvt_pk_bf16_f32 v232, v234, v235
	v_cvt_pk_bf16_f32 v233, v236, v237
	v_add_co_u32_e32 v236, vcc, 0x40000, v246
	v_addc_co_u32_e32 v237, vcc, 0, v247, vcc
	global_store_dwordx2 v[236:237], v[230:231], off
	global_store_dwordx2 v[236:237], v[232:233], off offset:32
	v_add_co_u32_e32 v236, vcc, 0x40100, v244
	v_addc_co_u32_e32 v237, vcc, 0, v245, vcc
	global_load_dwordx2 v[194:195], v[236:237], off
	global_load_dwordx2 v[196:197], v[236:237], off offset:32
	s_waitcnt vmcnt(0)
	v_lshlrev_b32_e32 v230, 16, v194
	v_and_b32_e32 v231, 0xffff0000, v194
	v_lshlrev_b32_e32 v232, 16, v195
	v_and_b32_e32 v233, 0xffff0000, v195
	v_pk_mul_f32 v[230:231], v[52:53], v[230:231]
	v_pk_mul_f32 v[232:233], v[54:55], v[232:233]
	v_cvt_pk_bf16_f32 v230, v230, v231
	v_cvt_pk_bf16_f32 v231, v232, v233
	v_lshlrev_b32_e32 v234, 16, v196
	v_and_b32_e32 v235, 0xffff0000, v196
	v_lshlrev_b32_e32 v236, 16, v197
	v_and_b32_e32 v237, 0xffff0000, v197
	v_pk_mul_f32 v[234:235], v[48:49], v[234:235]
	v_pk_mul_f32 v[236:237], v[50:51], v[236:237]
	v_cvt_pk_bf16_f32 v232, v234, v235
	v_cvt_pk_bf16_f32 v233, v236, v237
	v_add_co_u32_e32 v236, vcc, 0x40100, v246
	v_addc_co_u32_e32 v237, vcc, 0, v247, vcc
	global_store_dwordx2 v[236:237], v[230:231], off
	global_store_dwordx2 v[236:237], v[232:233], off offset:32
	v_add_co_u32_e32 v236, vcc, 0x48000, v244
	v_addc_co_u32_e32 v237, vcc, 0, v245, vcc
	global_load_dwordx2 v[194:195], v[236:237], off
	global_load_dwordx2 v[196:197], v[236:237], off offset:32
	s_waitcnt vmcnt(0)
	v_lshlrev_b32_e32 v230, 16, v194
	v_and_b32_e32 v231, 0xffff0000, v194
	v_lshlrev_b32_e32 v232, 16, v195
	v_and_b32_e32 v233, 0xffff0000, v195
	v_pk_mul_f32 v[230:231], v[44:45], v[230:231]
	v_pk_mul_f32 v[232:233], v[46:47], v[232:233]
	v_cvt_pk_bf16_f32 v230, v230, v231
	v_cvt_pk_bf16_f32 v231, v232, v233
	v_lshlrev_b32_e32 v234, 16, v196
	v_and_b32_e32 v235, 0xffff0000, v196
	v_lshlrev_b32_e32 v236, 16, v197
	v_and_b32_e32 v237, 0xffff0000, v197
	v_pk_mul_f32 v[234:235], v[40:41], v[234:235]
	v_pk_mul_f32 v[236:237], v[42:43], v[236:237]
	v_cvt_pk_bf16_f32 v232, v234, v235
	v_cvt_pk_bf16_f32 v233, v236, v237
	v_add_co_u32_e32 v236, vcc, 0x48000, v246
	v_addc_co_u32_e32 v237, vcc, 0, v247, vcc
	global_store_dwordx2 v[236:237], v[230:231], off
	global_store_dwordx2 v[236:237], v[232:233], off offset:32
	v_add_co_u32_e32 v236, vcc, 0x48100, v244
	v_addc_co_u32_e32 v237, vcc, 0, v245, vcc
	global_load_dwordx2 v[194:195], v[236:237], off
	global_load_dwordx2 v[196:197], v[236:237], off offset:32
	s_waitcnt vmcnt(0)
	v_lshlrev_b32_e32 v230, 16, v194
	v_and_b32_e32 v231, 0xffff0000, v194
	v_lshlrev_b32_e32 v232, 16, v195
	v_and_b32_e32 v233, 0xffff0000, v195
	v_pk_mul_f32 v[230:231], v[36:37], v[230:231]
	v_pk_mul_f32 v[232:233], v[38:39], v[232:233]
	v_cvt_pk_bf16_f32 v230, v230, v231
	v_cvt_pk_bf16_f32 v231, v232, v233
	v_lshlrev_b32_e32 v234, 16, v196
	v_and_b32_e32 v235, 0xffff0000, v196
	v_lshlrev_b32_e32 v236, 16, v197
	v_and_b32_e32 v237, 0xffff0000, v197
	v_pk_mul_f32 v[234:235], v[32:33], v[234:235]
	v_pk_mul_f32 v[236:237], v[34:35], v[236:237]
	v_cvt_pk_bf16_f32 v232, v234, v235
	v_cvt_pk_bf16_f32 v233, v236, v237
	v_add_co_u32_e32 v236, vcc, 0x48100, v246
	v_addc_co_u32_e32 v237, vcc, 0, v247, vcc
	global_store_dwordx2 v[236:237], v[230:231], off
	global_store_dwordx2 v[236:237], v[232:233], off offset:32
	v_add_co_u32_e32 v236, vcc, 0x50000, v244
	v_addc_co_u32_e32 v237, vcc, 0, v245, vcc
	global_load_dwordx2 v[194:195], v[236:237], off
	global_load_dwordx2 v[196:197], v[236:237], off offset:32
	s_waitcnt vmcnt(0)
	v_lshlrev_b32_e32 v230, 16, v194
	v_and_b32_e32 v231, 0xffff0000, v194
	v_lshlrev_b32_e32 v232, 16, v195
	v_and_b32_e32 v233, 0xffff0000, v195
	v_pk_mul_f32 v[230:231], v[28:29], v[230:231]
	v_pk_mul_f32 v[232:233], v[30:31], v[232:233]
	v_cvt_pk_bf16_f32 v230, v230, v231
	v_cvt_pk_bf16_f32 v231, v232, v233
	v_lshlrev_b32_e32 v234, 16, v196
	v_and_b32_e32 v235, 0xffff0000, v196
	v_lshlrev_b32_e32 v236, 16, v197
	v_and_b32_e32 v237, 0xffff0000, v197
	v_pk_mul_f32 v[234:235], v[24:25], v[234:235]
	v_pk_mul_f32 v[236:237], v[26:27], v[236:237]
	v_cvt_pk_bf16_f32 v232, v234, v235
	v_cvt_pk_bf16_f32 v233, v236, v237
	v_add_co_u32_e32 v236, vcc, 0x50000, v246
	v_addc_co_u32_e32 v237, vcc, 0, v247, vcc
	global_store_dwordx2 v[236:237], v[230:231], off
	global_store_dwordx2 v[236:237], v[232:233], off offset:32
	v_add_co_u32_e32 v236, vcc, 0x50100, v244
	v_addc_co_u32_e32 v237, vcc, 0, v245, vcc
	global_load_dwordx2 v[194:195], v[236:237], off
	global_load_dwordx2 v[196:197], v[236:237], off offset:32
	s_waitcnt vmcnt(0)
	v_lshlrev_b32_e32 v230, 16, v194
	v_and_b32_e32 v231, 0xffff0000, v194
	v_lshlrev_b32_e32 v232, 16, v195
	v_and_b32_e32 v233, 0xffff0000, v195
	v_pk_mul_f32 v[230:231], v[20:21], v[230:231]
	v_pk_mul_f32 v[232:233], v[22:23], v[232:233]
	v_cvt_pk_bf16_f32 v230, v230, v231
	v_cvt_pk_bf16_f32 v231, v232, v233
	v_lshlrev_b32_e32 v234, 16, v196
	v_and_b32_e32 v235, 0xffff0000, v196
	v_lshlrev_b32_e32 v236, 16, v197
	v_and_b32_e32 v237, 0xffff0000, v197
	v_pk_mul_f32 v[234:235], v[16:17], v[234:235]
	v_pk_mul_f32 v[236:237], v[18:19], v[236:237]
	v_cvt_pk_bf16_f32 v232, v234, v235
	v_cvt_pk_bf16_f32 v233, v236, v237
	v_add_co_u32_e32 v236, vcc, 0x50100, v246
	v_addc_co_u32_e32 v237, vcc, 0, v247, vcc
	global_store_dwordx2 v[236:237], v[230:231], off
	global_store_dwordx2 v[236:237], v[232:233], off offset:32
	v_add_co_u32_e32 v236, vcc, 0x58000, v244
	v_addc_co_u32_e32 v237, vcc, 0, v245, vcc
	global_load_dwordx2 v[194:195], v[236:237], off
	global_load_dwordx2 v[196:197], v[236:237], off offset:32
	s_waitcnt vmcnt(0)
	v_lshlrev_b32_e32 v230, 16, v194
	v_and_b32_e32 v231, 0xffff0000, v194
	v_lshlrev_b32_e32 v232, 16, v195
	v_and_b32_e32 v233, 0xffff0000, v195
	v_pk_mul_f32 v[230:231], v[12:13], v[230:231]
	v_pk_mul_f32 v[232:233], v[14:15], v[232:233]
	v_cvt_pk_bf16_f32 v230, v230, v231
	v_cvt_pk_bf16_f32 v231, v232, v233
	v_lshlrev_b32_e32 v234, 16, v196
	v_and_b32_e32 v235, 0xffff0000, v196
	v_lshlrev_b32_e32 v236, 16, v197
	v_and_b32_e32 v237, 0xffff0000, v197
	v_pk_mul_f32 v[234:235], v[8:9], v[234:235]
	v_pk_mul_f32 v[236:237], v[10:11], v[236:237]
	v_cvt_pk_bf16_f32 v232, v234, v235
	v_cvt_pk_bf16_f32 v233, v236, v237
	v_add_co_u32_e32 v236, vcc, 0x58000, v246
	v_addc_co_u32_e32 v237, vcc, 0, v247, vcc
	global_store_dwordx2 v[236:237], v[230:231], off
	global_store_dwordx2 v[236:237], v[232:233], off offset:32
	v_add_co_u32_e32 v236, vcc, 0x58100, v244
	v_addc_co_u32_e32 v237, vcc, 0, v245, vcc
	global_load_dwordx2 v[194:195], v[236:237], off
	global_load_dwordx2 v[196:197], v[236:237], off offset:32
	s_waitcnt vmcnt(0)
	v_lshlrev_b32_e32 v230, 16, v194
	v_and_b32_e32 v231, 0xffff0000, v194
	v_lshlrev_b32_e32 v232, 16, v195
	v_and_b32_e32 v233, 0xffff0000, v195
	v_pk_mul_f32 v[230:231], v[4:5], v[230:231]
	v_pk_mul_f32 v[232:233], v[6:7], v[232:233]
	v_cvt_pk_bf16_f32 v230, v230, v231
	v_cvt_pk_bf16_f32 v231, v232, v233
	v_lshlrev_b32_e32 v234, 16, v196
	v_and_b32_e32 v235, 0xffff0000, v196
	v_lshlrev_b32_e32 v236, 16, v197
	v_and_b32_e32 v237, 0xffff0000, v197
	v_pk_mul_f32 v[234:235], v[0:1], v[234:235]
	v_pk_mul_f32 v[236:237], v[2:3], v[236:237]
	v_cvt_pk_bf16_f32 v232, v234, v235
	v_cvt_pk_bf16_f32 v233, v236, v237
	v_add_co_u32_e32 v236, vcc, 0x58100, v246
	v_addc_co_u32_e32 v237, vcc, 0, v247, vcc
	global_store_dwordx2 v[236:237], v[230:231], off
	global_store_dwordx2 v[236:237], v[232:233], off offset:32
	s_branch .LBB0_1065
